# attention item table re-dealt assuming cheaper skipped subtiles (first-skip 0.5, later 0.2 of a full subtile)
# baseline (speedup 1.0000x reference)
.Ltbl:
	s_and_b32 s0, s73, 15
	s_mov_b32 s100, 0x403d77ef
	s_cmp_eq_u32 s0, 1
	s_cselect_b32 s100, 0x400686be, s100
	s_cmp_eq_u32 s0, 2
	s_cselect_b32 s100, 0x4038d4fc, s100
	s_cmp_eq_u32 s0, 3
	s_cselect_b32 s100, 0x40098937, s100
	s_cmp_eq_u32 s0, 4
	s_cselect_b32 s100, 0x402959a5, s100
	s_cmp_eq_u32 s0, 5
	s_cselect_b32 s100, 0x402127b3, s100
	s_cmp_eq_u32 s0, 6
	s_cselect_b32 s100, 0x401696f5, s100
	s_cmp_eq_u32 s0, 7
	s_cselect_b32 s100, 0x40309ab6, s100
	s_cmp_eq_u32 s0, 8
	s_cselect_b32 s100, 0x401b8e7f, s100
	s_cmp_eq_u32 s0, 9
	s_cselect_b32 s100, 0x40021ebb, s100
	s_cmp_eq_u32 s0, 10
	s_cselect_b32 s100, 0x40411774, s100
	s_cmp_eq_u32 s0, 11
	s_cselect_b32 s100, 0x401318ec, s100
	s_cmp_eq_u32 s0, 12
	s_cselect_b32 s100, 0x400e0bad, s100
	s_cmp_eq_u32 s0, 13
	s_cselect_b32 s100, 0x402f067d, s100
	s_cmp_eq_u32 s0, 14
	s_cselect_b32 s100, 0x40516727, s100
	s_cmp_eq_u32 s0, 15
	s_cselect_b32 s100, 0x401e2cab, s100
	s_mov_b32 s74, 0
